# attention loop: LDS-DMA addressed as scalar tile base + per-lane 32-bit offset; per-tile pointer advance is 2 SALU instead of 3 64-bit VALU adds
# speedup vs baseline: 1.0048x; 1.0036x over previous
; #define SBAR() __builtin_amdgcn_sched_barrier(0)
; template<int THRL> __device__ __forceinline__ void attn_unit(int qb,const bf16*Q,const bf16*__restrict__ K,const bf16*__restrict__ V,bf16*O,char*shm){
;     ...
;     float a=MX3(C0[0],C0[1],C1[0]),b=MX3(C0[2],C0[3],C1[1]); a=MX3(a,C1[2],C1[3]);
;     #pragma unroll
;     for(int r=4;r<16;r+=4){a=MX3(a,C0[r],C0[r+1]);b=MX3(b,C0[r+2],C0[r+3]);a=MX3(a,C1[r],C1[r+1]);b=MX3(b,C1[r+2],C1[r+3]);}
;     float rm=__builtin_fmaxf(a,b); { auto rr=__builtin_amdgcn_permlane32_swap(__float_as_uint(rm),__float_as_uint(rm),false,false); rm=__builtin_fmaxf(__uint_as_float(rr[0]),__uint_as_float(rr[1])); }
;     if(t==0 || __any(rm>(float)THRL)){
;       const float dl=(t==0)?rm:__builtin_fmaxf(rm,0.f); mhat+=dl;
;       #pragma unroll
;       for(int r=0;r<16;++r){C0[r]-=dl;C1[r]-=dl;}
;       #pragma unroll
;       for(int r=0;r<16;++r)negm[r]=-mhat;
;       if(t!=0){ const float f=__builtin_amdgcn_exp2f(-dl); l_reg*=f; if(hi==0)wsf[r32]=f; asm volatile("s_waitcnt lgkmcnt(0)":::"memory");
;         #pragma unroll
;         for(int d_=0;d_<4;++d_)
;           #pragma unroll
;           for(int r=0;r<16;++r)o[d_][r]*=wsf[crow(r,hi)]; } }
;     #pragma unroll
;     for(int r=0;r<16;++r){C0[r]=__builtin_amdgcn_exp2f(C0[r]);C1[r]=__builtin_amdgcn_exp2f(C1[r]);}
;     { float s0=C0[0]+C0[1],s1=C1[0]+C1[1];
;       #pragma unroll
;       for(int r=2;r<16;++r){s0+=C0[r];s1+=C1[r];}
;       l_reg+=s0+s1; }
;     const u32x4 pw0=(u32x4){PKW(C0,0),PKW(C0,2),PKW(C0,4),PKW(C0,6)},pw1=(u32x4){PKW(C0,8),PKW(C0,10),PKW(C0,12),PKW(C0,14)},pw2=(u32x4){PKW(C1,0),PKW(C1,2),PKW(C1,4),PKW(C1,6)},pw3=(u32x4){PKW(C1,8),PKW(C1,10),PKW(C1,12),PKW(C1,14)};
;     SBAR();
;     ...
;     s16x4 w2l_[4],w2h_[4],w3l_[4],w3h_[4];
;     #pragma unroll
;     for(int d_=0;d_<4;++d_){ w2l_[d_]=vtr(vp_+(d_*4096+2*1024)); w2h_[d_]=vtr(vp_+(d_*4096+2*1024+512)); }
;     SBAR();
;     #pragma unroll
;     for(int d_=0;d_<4;++d_){ o[d_]=__builtin_amdgcn_mfma_f32_32x32x16_bf16(__builtin_bit_cast(bf16x8,pw0),VFRAG(vl_,vh_,d_*2),o[d_],0,0,0); }
;     SBAR();
;     #pragma unroll
;     for(int d_=0;d_<4;++d_){ w3l_[d_]=vtr(vp_+(d_*4096+3*1024)); w3h_[d_]=vtr(vp_+(d_*4096+3*1024+512)); }
;     SBAR();
;     #pragma unroll
;     for(int d_=0;d_<4;++d_){ o[d_]=__builtin_amdgcn_mfma_f32_32x32x16_bf16(__builtin_bit_cast(bf16x8,pw1),VFRAG(vl_,vh_,d_*2+1),o[d_],0,0,0); }
;     #pragma unroll
.LBB0_363:
	v_max_f32_e32 v40, v1, v1
	v_max_f32_e32 v41, v0, v0
	v_max_f32_e32 v40, v41, v40
	s_nop 6
	v_max3_f32 v41, v2, v3, v17
	v_max3_f32 v40, v40, v16, v18
	v_max3_f32 v40, v40, v19, v4
	v_max3_f32 v41, v41, v6, v7
	v_max3_f32 v40, v40, v5, v20
	v_max3_f32 v41, v41, v22, v23
	v_max3_f32 v40, v40, v21, v8
	v_max3_f32 v41, v41, v10, v11
	v_max3_f32 v40, v40, v9, v24
	v_max3_f32 v41, v41, v26, v27
	v_max3_f32 v40, v40, v25, v12
	v_max3_f32 v41, v41, v14, v15
	v_max3_f32 v40, v40, v13, v28
	v_max3_f32 v41, v41, v30, v31
	v_max3_f32 v40, v40, v29, v41
	v_mov_b32_e32 v41, v40
	s_nop 1
	v_permlane32_swap_b32_e32 v40, v41
	v_max_f32_e32 v41, v41, v41
	v_max_f32_e32 v40, v40, v40
	v_max_f32_e32 v64, v40, v41
	v_sub_f32_e32 v16, v16, v64
	v_sub_f32_e32 v17, v17, v64
	v_sub_f32_e32 v0, v0, v64
	v_sub_f32_e32 v1, v1, v64
	v_sub_f32_e32 v18, v18, v64
	v_sub_f32_e32 v40, v27, v64
	v_sub_f32_e32 v41, v29, v64
	v_sub_f32_e32 v42, v30, v64
	v_sub_f32_e32 v44, v31, v64
	v_sub_f32_e32 v2, v2, v64
	v_sub_f32_e32 v27, v4, v64
	v_sub_f32_e32 v29, v5, v64
	v_sub_f32_e32 v30, v6, v64
	v_sub_f32_e32 v31, v7, v64
	v_exp_f32_e32 v5, v0
	v_exp_f32_e32 v4, v16
	v_exp_f32_e32 v7, v1
	v_exp_f32_e32 v6, v17
	v_sub_f32_e32 v19, v19, v64
	v_sub_f32_e32 v3, v3, v64
	v_sub_f32_e32 v43, v8, v64
	v_sub_f32_e32 v45, v9, v64
	v_exp_f32_e32 v9, v2
	v_exp_f32_e32 v8, v18
	v_sub_f32_e32 v20, v20, v64
	v_sub_f32_e32 v46, v10, v64
	v_sub_f32_e32 v47, v11, v64
	v_exp_f32_e32 v11, v3
	v_exp_f32_e32 v10, v19
	v_sub_f32_e32 v21, v21, v64
	v_sub_f32_e32 v48, v12, v64
	v_sub_f32_e32 v49, v13, v64
	v_exp_f32_e32 v13, v27
	v_exp_f32_e32 v12, v20
	v_sub_f32_e32 v22, v22, v64
	v_sub_f32_e32 v50, v14, v64
	v_sub_f32_e32 v51, v15, v64
	v_exp_f32_e32 v15, v29
	v_exp_f32_e32 v14, v21
	v_pk_add_f32 v[0:1], v[4:5], v[6:7]
	v_sub_f32_e32 v23, v23, v64
	v_exp_f32_e32 v17, v30
	v_exp_f32_e32 v16, v22
	v_pk_add_f32 v[0:1], v[8:9], v[0:1]
	v_sub_f32_e32 v24, v24, v64
	v_exp_f32_e32 v19, v31
	v_exp_f32_e32 v18, v23
	v_pk_add_f32 v[0:1], v[10:11], v[0:1]
	v_sub_f32_e32 v25, v25, v64
	v_exp_f32_e32 v21, v43
	v_exp_f32_e32 v20, v24
	v_pk_add_f32 v[0:1], v[12:13], v[0:1]
	v_sub_f32_e32 v26, v26, v64
	v_exp_f32_e32 v23, v45
	v_exp_f32_e32 v22, v25
	v_pk_add_f32 v[0:1], v[14:15], v[0:1]
	v_exp_f32_e32 v25, v46
	v_exp_f32_e32 v24, v26
	v_pk_add_f32 v[0:1], v[16:17], v[0:1]
	v_sub_f32_e32 v28, v28, v64
	v_exp_f32_e32 v27, v47
	v_exp_f32_e32 v26, v40
	v_pk_add_f32 v[0:1], v[18:19], v[0:1]
	v_exp_f32_e32 v29, v48
	v_exp_f32_e32 v28, v28
	v_pk_add_f32 v[0:1], v[20:21], v[0:1]
	v_exp_f32_e32 v31, v49
	v_exp_f32_e32 v30, v41
	v_pk_add_f32 v[0:1], v[22:23], v[0:1]
	v_exp_f32_e32 v41, v50
	v_exp_f32_e32 v40, v42
	v_pk_add_f32 v[0:1], v[24:25], v[0:1]
	v_exp_f32_e32 v43, v51
	v_exp_f32_e32 v42, v44
	v_pk_add_f32 v[0:1], v[26:27], v[0:1]
	v_cmp_gt_u32_e64 s[4:5], 32, v186
	v_pk_add_f32 v[0:1], v[28:29], v[0:1]
	s_mov_b32 s27, 2
	v_pk_add_f32 v[0:1], v[30:31], v[0:1]
	v_lshl_add_u32 v191, v177, 2, s25
	v_pk_add_f32 v[0:1], v[40:41], v[0:1]
	v_cvt_pk_bf16_f32 v2, v13, v15
	v_pk_add_f32 v[0:1], v[42:43], v[0:1]
	v_cvt_pk_bf16_f32 v3, v17, v19
	v_pk_add_f32 v[110:111], v[0:1], v[0:1] op_sel_hi:[0,1]
	v_cvt_pk_bf16_f32 v0, v5, v7
	v_cvt_pk_bf16_f32 v1, v9, v11
	v_lshlrev_b32_e32 v148, 4, v175
	v_cvt_pk_bf16_f32 v94, v21, v23
	v_cvt_pk_bf16_f32 v95, v25, v27
	v_cvt_pk_bf16_f32 v96, v29, v31
	v_cvt_pk_bf16_f32 v97, v41, v43
	v_cvt_pk_bf16_f32 v98, v4, v6
	v_cvt_pk_bf16_f32 v99, v8, v10
	v_cvt_pk_bf16_f32 v100, v12, v14
	v_cvt_pk_bf16_f32 v101, v16, v18
	v_cvt_pk_bf16_f32 v102, v20, v22
	v_cvt_pk_bf16_f32 v103, v24, v26
	v_cvt_pk_bf16_f32 v104, v28, v30
	v_cvt_pk_bf16_f32 v105, v40, v42
	ds_read_b64_tr_b16 v[106:107], v190 offset:26624
	ds_read_b64_tr_b16 v[108:109], v190 offset:27136
	ds_read_b64_tr_b16 v[128:129], v190 offset:30720
	ds_read_b64_tr_b16 v[130:131], v190 offset:31232
	ds_read_b64_tr_b16 v[132:133], v190 offset:34816
	ds_read_b64_tr_b16 v[134:135], v190 offset:35328
	ds_read_b64_tr_b16 v[136:137], v190 offset:38912
	ds_read_b64_tr_b16 v[138:139], v190 offset:39424
	v_mfma_f32_32x32x16_bf16 v[48:63], v[0:3], v[36:39], 0
	v_mov_b32_e32 v65, v111
	v_add_f32_e64 v178, v64, 0
	v_add_f32_e64 v179, v65, 0
	v_add_f32_e64 v64, -v178, neg(0)
	v_add_f32_e64 v65, -v179, neg(0)
	s_waitcnt lgkmcnt(14)
	v_mfma_f32_32x32x16_bf16 v[32:47], v[0:3], v[32:35], 0
	v_mfma_f32_32x32x16_bf16 v[16:31], v[0:3], v[82:85], 0
	s_waitcnt lgkmcnt(10)
	v_mfma_f32_32x32x16_bf16 v[0:15], v[0:3], v[86:89], 0
	ds_read_b64_tr_b16 v[82:83], v190 offset:27648
	ds_read_b64_tr_b16 v[84:85], v190 offset:28160
	ds_read_b64_tr_b16 v[86:87], v190 offset:31744
	ds_read_b64_tr_b16 v[88:89], v190 offset:32256
	ds_read_b64_tr_b16 v[140:141], v190 offset:35840
	ds_read_b64_tr_b16 v[142:143], v190 offset:36352
	ds_read_b64_tr_b16 v[144:145], v190 offset:39936
	ds_read_b64_tr_b16 v[146:147], v190 offset:40448
	v_mfma_f32_32x32x16_bf16 v[48:63], v[94:97], v[78:81], v[48:63]
	v_mfma_f32_32x32x16_bf16 v[32:47], v[94:97], v[74:77], v[32:47]
	v_mfma_f32_32x32x16_bf16 v[16:31], v[94:97], v[70:73], v[16:31]
	s_waitcnt lgkmcnt(14)
	v_mfma_f32_32x32x16_bf16 v[0:15], v[94:97], v[66:69], v[0:15]
	v_mfma_f32_32x32x16_bf16 v[48:63], v[98:101], v[106:109], v[48:63]
	s_waitcnt lgkmcnt(12)
	v_mfma_f32_32x32x16_bf16 v[32:47], v[98:101], v[128:131], v[32:47]
	s_waitcnt lgkmcnt(10)
	v_mfma_f32_32x32x16_bf16 v[16:31], v[98:101], v[132:135], v[16:31]
	s_waitcnt lgkmcnt(8)
	v_mfma_f32_32x32x16_bf16 v[0:15], v[98:101], v[136:139], v[0:15]
	s_waitcnt lgkmcnt(6)
	v_mfma_f32_32x32x16_bf16 v[48:63], v[102:105], v[82:85], v[48:63]
	s_waitcnt lgkmcnt(4)
	v_mfma_f32_32x32x16_bf16 v[32:47], v[102:105], v[86:89], v[32:47]
	s_waitcnt lgkmcnt(2)
	v_mfma_f32_32x32x16_bf16 v[16:31], v[102:105], v[140:143], v[16:31]
	s_waitcnt lgkmcnt(0)
	v_mfma_f32_32x32x16_bf16 v[0:15], v[102:105], v[144:147], v[0:15]
	ds_read_b128 v[236:239], v189 offset:8192
	ds_read_b128 v[128:131], v189 offset:8704
	ds_read_b128 v[240:243], v189 offset:10240
	ds_read_b128 v[132:135], v189 offset:10752
	ds_read_b128 v[244:247], v189 offset:12288
	ds_read_b128 v[144:147], v189 offset:12800
	ds_read_b128 v[248:251], v189 offset:14336
	ds_read_b128 v[194:197], v189 offset:14848
	s_lshl_b32 s31, s26, 6
	s_sub_i32 s28, 0, s26
	v_subrev_u32_e32 v65, s31, v93
	s_lshl_b64 s[14:15], s[14:15], 1
	v_add_u32_e32 v192, 0x17b, v65
	v_and_b32_e32 v65, 3, v92
	s_add_u32 s12, s14, s12
	v_lshlrev_b32_e32 v66, 4, v65
	v_mov_b32_e32 v67, v161
	s_addc_u32 s13, s15, s13
	s_waitcnt vmcnt(2) lgkmcnt(0)
	s_barrier
;   #define DMA_K(t,s3) glds16(ksrc+(long)(t)*KVBLK*DM,(unsigned)__builtin_amdgcn_readfirstlane(kdst+(s3)*SLOTB))
;   #define DMA_V(t,s3) do{ const unsigned vd_=(unsigned)__builtin_amdgcn_readfirstlane(vdst+(s3)*VSLOTB); glds16(vsrc+(long)(t)*KVBLK*DM,vd_); glds16(vsrc+(long)(t)*KVBLK*DM+64,(unsigned)__builtin_amdgcn_readfirstlane(vd_+8192)); }while(0)
; template<int THRL> __device__ __forceinline__ void attn_unit(int qb,const bf16*Q,const bf16*__restrict__ K,const bf16*__restrict__ V,bf16*O,char*shm){
;     ...
;   const bf16*ksrc=K+(long)lane*DM+wid*8;
;   const bf16*vsrc=V+(long)(16*(wid&3)+(lane>>2))*DM+(wid>>2)*32+(lane&3)*8;
;   const unsigned kdst=lds0+LDS_K+wid*1024, vdst=lds0+LDS_V+wid*1024;
;     ...
;   const lds_cptr shm3=(lds_cptr)shm;
;   const int NT=(q0+QB)/KVBLK;
;   DMA_K(0,0);DMA_V(0,0);DMA_K(1,1);DMA_V(1,1);
	v_lshl_add_u64 v[66:67], s[12:13], 0, v[66:67]
	v_lshl_add_u64 v[66:67], v[66:67], 0, v[160:161]
	s_mov_b64 s[12:13], 0xc6000
	s_mov_b32 s29, 0
	s_mov_b32 s35, 1
	v_lshl_add_u64 v[180:181], s[6:7], 0, v[66:67]
	v_lshl_add_u64 v[182:183], v[90:91], 0, s[12:13]
	s_mov_b32 m0, s9
	s_nop 0
	global_load_lds_dwordx4 v[182:183], off
	v_lshl_add_u64 v[182:183], v[182:183], 0, s[88:89]
	v_subrev_u32_e32 v180, s38, v180
	v_subrev_u32_e32 v182, s38, v182
	v_add_u32_e32 v165, s50, v180
	s_mov_b64 s[100:101], s[38:39]
	v_add_u32_e32 v160, s25, v148
	s_mov_b32 s31, 1
	v_mov_b32_e32 v65, v64
	v_mov_b32_e32 v66, v64
	v_mov_b32_e32 v67, v64
	v_mov_b32_e32 v68, v64
	v_mov_b32_e32 v69, v64
	v_mov_b32_e32 v70, v64
	v_mov_b32_e32 v71, v64
	v_mov_b32_e32 v72, v64
	v_mov_b32_e32 v73, v64
	v_mov_b32_e32 v74, v64
	v_mov_b32_e32 v75, v64
	v_mov_b32_e32 v76, v64
	v_mov_b32_e32 v77, v64
	v_mov_b32_e32 v78, v64
	v_mov_b32_e32 v79, v64

; #define SBAR() __builtin_amdgcn_sched_barrier(0)
; #define WAIT_BAR(N) asm volatile("s_waitcnt vmcnt(" #N ") lgkmcnt(0)\n\ts_barrier":::"memory")
; __device__ __forceinline__ s16x4 vtr(lds_cptr p){ return __builtin_bit_cast(s16x4,__builtin_amdgcn_ds_read_tr16_b64_v4i16((__attribute__((address_space(3))) v4i16_t*)p)); }
;   #define ROT3() do{ const int x_=c0; c0=c1; c1=c2; c2=x_; }while(0)
;   #define PKW(P,B) cvtpk_s(P[B],P[B+1])
; template<int THRL> __device__ __forceinline__ void attn_unit(int qb,const bf16*Q,const bf16*__restrict__ K,const bf16*__restrict__ V,bf16*O,char*shm){
;     ...
;     #pragma unroll
;     for(int r=0;r<16;++r){C0[r]=__builtin_amdgcn_exp2f(C0[r]);C1[r]=__builtin_amdgcn_exp2f(C1[r]);}
;     { float s0=C0[0]+C0[1],s1=C1[0]+C1[1];
;       #pragma unroll
;       for(int r=2;r<16;++r){s0+=C0[r];s1+=C1[r];}
;       l_reg+=s0+s1; }
;     const u32x4 pw0=(u32x4){PKW(C0,0),PKW(C0,2),PKW(C0,4),PKW(C0,6)},pw1=(u32x4){PKW(C0,8),PKW(C0,10),PKW(C0,12),PKW(C0,14)},pw2=(u32x4){PKW(C1,0),PKW(C1,2),PKW(C1,4),PKW(C1,6)},pw3=(u32x4){PKW(C1,8),PKW(C1,10),PKW(C1,12),PKW(C1,14)};
;     SBAR();
;     ...
;     s16x4 w2l_[4],w2h_[4],w3l_[4],w3h_[4];
;     #pragma unroll
;     for(int d_=0;d_<4;++d_){ w2l_[d_]=vtr(vp_+(d_*4096+2*1024)); w2h_[d_]=vtr(vp_+(d_*4096+2*1024+512)); }
;     SBAR();
;     #pragma unroll
;     for(int d_=0;d_<4;++d_){ o[d_]=__builtin_amdgcn_mfma_f32_32x32x16_bf16(__builtin_bit_cast(bf16x8,pw0),VFRAG(vl_,vh_,d_*2),o[d_],0,0,0); }
;     SBAR();
;     #pragma unroll
;     for(int d_=0;d_<4;++d_){ w3l_[d_]=vtr(vp_+(d_*4096+3*1024)); w3h_[d_]=vtr(vp_+(d_*4096+3*1024+512)); }
;     SBAR();
;     #pragma unroll
;     for(int d_=0;d_<4;++d_){ o[d_]=__builtin_amdgcn_mfma_f32_32x32x16_bf16(__builtin_bit_cast(bf16x8,pw1),VFRAG(vl_,vh_,d_*2+1),o[d_],0,0,0); }
;     #pragma unroll
;     for(int d_=0;d_<4;++d_){ o[d_]=__builtin_amdgcn_mfma_f32_32x32x16_bf16(__builtin_bit_cast(bf16x8,pw2),VFRAG(w2l_,w2h_,d_),o[d_],0,0,0); }
;     #pragma unroll
;     for(int d_=0;d_<4;++d_){ o[d_]=__builtin_amdgcn_mfma_f32_32x32x16_bf16(__builtin_bit_cast(bf16x8,pw3),VFRAG(w3l_,w3h_,d_),o[d_],0,0,0); }
;     SBAR();
;     ...
;     if(t+2<NT){WAIT_BAR(3);}else{WAIT_BAR(0);}
;     ROT3();
.LBB0_372:
	v_exp_f32_e32 v80, v80
	v_exp_f32_e32 v81, v81
	v_exp_f32_e32 v82, v82
	v_exp_f32_e32 v83, v83
	v_exp_f32_e32 v84, v84
	v_exp_f32_e32 v85, v85
	v_exp_f32_e32 v86, v86
	v_exp_f32_e32 v87, v87
	ds_read_b64_tr_b16 v[210:211], v193 offset:26624
	ds_read_b64_tr_b16 v[212:213], v193 offset:27136
	v_cvt_pk_bf16_f32 v194, v80, v81
	v_cvt_pk_bf16_f32 v195, v82, v83
	v_cvt_pk_bf16_f32 v196, v84, v85
	v_cvt_pk_bf16_f32 v197, v86, v87
	s_and_b64 vcc, exec, s[12:13]
	v_exp_f32_e32 v88, v88
	v_exp_f32_e32 v89, v89
	s_waitcnt lgkmcnt(15)
	v_mfma_f32_32x32x16_bf16 v[48:63], v[194:197], v[156:159], v[48:63]
	ds_read_b64_tr_b16 v[214:215], v193 offset:30720
	ds_read_b64_tr_b16 v[216:217], v193 offset:31232
	v_exp_f32_e32 v90, v90
	v_exp_f32_e32 v91, v91
	v_cvt_pk_bf16_f32 v198, v88, v89
	s_waitcnt lgkmcnt(14)
	v_mfma_f32_32x32x16_bf16 v[32:47], v[194:197], v[152:155], v[32:47]
	ds_read_b64_tr_b16 v[218:219], v193 offset:34816
	ds_read_b64_tr_b16 v[220:221], v193 offset:35328
	v_exp_f32_e32 v92, v92
	v_exp_f32_e32 v93, v93
	v_cvt_pk_bf16_f32 v199, v90, v91
	s_cbranch_vccnz .Lattn_nodma0
	s_lshl_b32 s14, s34, 13
	s_add_i32 s14, s14, s9
	s_mov_b32 m0, s14
	s_nop 0
	global_load_lds_dwordx4 v182, s[100:101]
.Lattn_nodma0:
	s_waitcnt lgkmcnt(12)
	v_mfma_f32_32x32x16_bf16 v[16:31], v[194:197], v[148:151], v[16:31]
	ds_read_b64_tr_b16 v[232:233], v193 offset:38912
	ds_read_b64_tr_b16 v[234:235], v193 offset:39424
	v_exp_f32_e32 v94, v94
	v_exp_f32_e32 v95, v95
	v_cvt_pk_bf16_f32 v200, v92, v93
	v_lshl_add_u32 v164, s27, 13, v189
	s_waitcnt lgkmcnt(10)
	v_mfma_f32_32x32x16_bf16 v[0:15], v[194:197], v[144:147], v[0:15]
	ds_read_b64_tr_b16 v[156:157], v193 offset:39936
	ds_read_b64_tr_b16 v[158:159], v193 offset:40448
	ds_read_b128 v[236:239], v164
	v_cvt_pk_bf16_f32 v201, v94, v95
	v_exp_f32_e32 v96, v96
	v_exp_f32_e32 v97, v97
	v_mfma_f32_32x32x16_bf16 v[48:63], v[198:201], v[140:143], v[48:63]
	ds_read_b64_tr_b16 v[152:153], v193 offset:35840
	ds_read_b64_tr_b16 v[154:155], v193 offset:36352
	ds_read_b128 v[240:243], v164 offset:2048
	v_exp_f32_e32 v98, v98
	v_exp_f32_e32 v99, v99
	v_cvt_pk_bf16_f32 v202, v96, v97
	v_add_f32_e32 v80, v80, v81
	v_mfma_f32_32x32x16_bf16 v[32:47], v[198:201], v[136:139], v[32:47]
	ds_read_b64_tr_b16 v[148:149], v193 offset:31744
	ds_read_b64_tr_b16 v[150:151], v193 offset:32256
	ds_read_b128 v[244:247], v164 offset:4096
	v_exp_f32_e32 v100, v100
	v_exp_f32_e32 v101, v101
	v_cvt_pk_bf16_f32 v203, v98, v99
	v_add_f32_e32 v80, v82, v80
	s_add_i32 s14, s31, 2
	s_cmp_ge_i32 s14, s26
	s_cbranch_scc1 .Lattn_nodma1
	s_lshl_b32 s14, s29, 14
	s_add_i32 s14, s14, s11
	s_mov_b32 m0, s14
	s_nop 0
	global_load_lds_dwordx4 v180, s[100:101]
.Lattn_nodma1:
	v_mfma_f32_32x32x16_bf16 v[16:31], v[198:201], v[132:135], v[16:31]
	ds_read_b64_tr_b16 v[144:145], v193 offset:27648
	ds_read_b64_tr_b16 v[146:147], v193 offset:28160
	ds_read_b128 v[248:251], v164 offset:6144
	v_exp_f32_e32 v102, v102
	v_exp_f32_e32 v103, v103
	v_cvt_pk_bf16_f32 v204, v100, v101
	v_add_f32_e32 v80, v83, v80
	s_waitcnt lgkmcnt(15)
	v_mfma_f32_32x32x16_bf16 v[0:15], v[198:201], v[128:131], v[0:15]
	ds_read_b128 v[194:197], v164 offset:6656
	v_cvt_pk_bf16_f32 v205, v102, v103
	v_exp_f32_e32 v104, v104
	v_exp_f32_e32 v105, v105
	v_add_f32_e32 v80, v84, v80
	v_mfma_f32_32x32x16_bf16 v[48:63], v[202:205], v[210:213], v[48:63]
	ds_read_b128 v[132:135], v164 offset:2560
	v_exp_f32_e32 v106, v106
	v_exp_f32_e32 v107, v107
	v_cvt_pk_bf16_f32 v206, v104, v105
	v_add_f32_e32 v80, v85, v80
	v_mfma_f32_32x32x16_bf16 v[32:47], v[202:205], v[214:217], v[32:47]
	s_add_i32 s14, s31, 2
	s_cmp_ge_i32 s14, s26
	s_cbranch_scc1 .Lattn_nodma2
	s_lshl_b32 s14, s29, 14
	s_add_i32 s14, s14, s11
	s_addk_i32 s14, 0x2000
	s_mov_b32 m0, s14
	s_nop 0
	global_load_lds_dwordx4 v165, s[100:101]
.Lattn_nodma2:
	ds_read_b128 v[128:131], v164 offset:512
	v_exp_f32_e32 v108, v108
	v_exp_f32_e32 v109, v109
	v_cvt_pk_bf16_f32 v207, v106, v107
	v_add_f32_e32 v80, v86, v80
	s_waitcnt lgkmcnt(15)
	v_mfma_f32_32x32x16_bf16 v[16:31], v[202:205], v[218:221], v[16:31]
	v_exp_f32_e32 v110, v110
	v_exp_f32_e32 v111, v111
	v_cvt_pk_bf16_f32 v208, v108, v109
	v_add_f32_e32 v80, v87, v80
	v_mfma_f32_32x32x16_bf16 v[0:15], v[202:205], v[232:235], v[0:15]
	v_cvt_pk_bf16_f32 v209, v110, v111
	v_add_f32_e32 v81, v96, v97
	v_add_f32_e32 v80, v88, v80
	v_add_f32_e32 v81, v98, v81
	v_add_u32_e32 v192, 64, v192
	s_add_u32 s100, s100, s88
	s_addc_u32 s101, s101, s89
	s_waitcnt lgkmcnt(4)
	v_mfma_f32_32x32x16_bf16 v[48:63], v[206:209], v[144:147], v[48:63]
	ds_read_b128 v[144:147], v164 offset:4608
	v_add_f32_e32 v80, v89, v80
	v_add_f32_e32 v81, v99, v81
	v_add_f32_e32 v80, v90, v80
	v_add_f32_e32 v81, v100, v81
	v_add_f32_e32 v80, v91, v80
	v_add_f32_e32 v81, v101, v81
	s_add_i32 s31, s31, 1
	s_lshl_b32 s14, s27, 14
	v_add_u32_e32 v193, s14, v190
	v_mfma_f32_32x32x16_bf16 v[32:47], v[206:209], v[148:151], v[32:47]
	v_add_f32_e32 v80, v92, v80
	v_add_f32_e32 v81, v102, v81
	v_add_f32_e32 v80, v93, v80
	v_add_f32_e32 v81, v103, v81
	v_add_f32_e32 v80, v94, v80
	v_add_f32_e32 v81, v104, v81
	s_mov_b32 s35, s27
	s_mov_b32 s27, s29
	s_mov_b32 s29, s34
	s_mov_b32 s34, s35
	v_mfma_f32_32x32x16_bf16 v[16:31], v[206:209], v[152:155], v[16:31]
	v_add_f32_e32 v80, v95, v80
	v_add_f32_e32 v81, v105, v81
	v_add_f32_e32 v81, v106, v81
	v_add_f32_e32 v81, v107, v81
	v_add_f32_e32 v81, v108, v81
	v_add_f32_e32 v81, v109, v81
	s_add_i32 s12, s31, 3
	s_cmp_ge_i32 s12, s26
	s_cselect_b64 s[12:13], -1, 0
	v_mfma_f32_32x32x16_bf16 v[0:15], v[206:209], v[156:159], v[0:15]
	v_add_f32_e32 v81, v110, v81
	v_add_f32_e32 v81, v111, v81
	v_add_f32_e32 v80, v81, v80
	v_add_f32_e32 v179, v179, v80
	s_add_i32 s14, s28, s31
	s_cbranch_vccnz .Lattn_tailbar
	s_cmp_eq_u32 s14, 0
	s_waitcnt vmcnt(3) lgkmcnt(0)
	s_barrier
	s_cbranch_scc0 .Lattn_top
	s_branch .LBB0_379
